# attention kv loop: cross-half row-max exchange via v_permlane32_swap in registers instead of ds_bpermute_b32 (removes an LDS round trip from the serial softmax chain of every tile)
# speedup vs baseline: 1.0019x; 1.0019x over previous
; #define MFMA(a, b, c) __builtin_amdgcn_mfma_f32_32x32x16_bf16((a), (b), (c), 0, 0, 0)
; DI void phase4(const Params& p, char* smem) {
;     ...
;         if (kt < c) load_tile();
;         f32x16 s;
; #pragma unroll
;         for (int i = 0; i < 16; ++i) s[i] = 0.f;
;         const u16* kp = Ks + (kh * 32 + r) * 200 + hi * 8;
;         {
;           bf16x8 kf[4];
; #pragma unroll
;           for (int i = 0; i < 4; ++i) kf[i] = *(const bf16x8*)(kp + i * 16);
; #pragma unroll
;           for (int ks = 0; ks < 12; ++ks) {
;             __builtin_amdgcn_sched_barrier(0);
;             s = MFMA(kf[ks & 3], qf[ks], s);
;             if (ks + 4 < 12) kf[ks & 3] = *(const bf16x8*)(kp + (ks + 4) * 16);
;           }
;           __builtin_amdgcn_sched_barrier(0);
;         }
;         bf16x8 vf0[4];
; #pragma unroll
;         for (int dt = 0; dt < 4; ++dt) {
;           const u16* vp = Vs + (dt * 32 + r) * 68 + kh * 32 + 4 * hi;
;           const u32x2 v0 = *(const u32x2*)vp, v1 = *(const u32x2*)(vp + 8);
;           const u32x4 vv = {v0[0], v0[1], v1[0], v1[1]};
;           vf0[dt] = __builtin_bit_cast(bf16x8, vv);
;         }
;         float mx = s[0];
; #pragma unroll
;         for (int i = 1; i < 16; ++i) mx = fmaxf(mx, s[i]);
;         mx = fmaxf(mx, __shfl_xor(mx, 32));
;         const float mn = fmaxf(m, mx);
;         const float alpha = __builtin_amdgcn_exp2f(m - mn);
;         const bool resc = __builtin_amdgcn_ballot_w64(mn > m) != 0ull;
;         m = mn;
;         float rsum = 0.f;
; #pragma unroll
;         for (int i = 0; i < 16; ++i) { s[i] = __builtin_amdgcn_exp2f(s[i] - mn); rsum += s[i]; }
;         l = l * alpha + rsum;
;         if (resc) {
; #pragma unroll
;           for (int dt = 0; dt < 4; ++dt)
; #pragma unroll
;             for (int i = 0; i < 16; ++i) O[dt][i] *= alpha;
;         }
.LBB0_642:
	ds_read_b128 v[68:71], v225 offset:16
	ds_read_b128 v[172:175], v225 offset:48
	ds_read_b128 v[176:179], v225 offset:80
	ds_read_b128 v[180:183], v225 offset:112
	s_waitcnt lgkmcnt(3)
	v_mfma_f32_32x32x16_bf16 v[68:83], v[68:71], v[84:87], 0
	ds_read_b128 v[184:187], v225 offset:144
	s_waitcnt lgkmcnt(3)
	v_mfma_f32_32x32x16_bf16 v[68:83], v[172:175], v[88:91], v[68:83]
	ds_read_b128 v[232:235], v225 offset:176
	s_waitcnt lgkmcnt(3)
	v_mfma_f32_32x32x16_bf16 v[68:83], v[176:179], v[92:95], v[68:83]
	ds_read_b128 v[172:175], v225 offset:208
	s_waitcnt lgkmcnt(3)
	v_mfma_f32_32x32x16_bf16 v[68:83], v[180:183], v[96:99], v[68:83]
	ds_read_b128 v[176:179], v225 offset:240
	s_waitcnt lgkmcnt(3)
	v_mfma_f32_32x32x16_bf16 v[68:83], v[184:187], v[100:103], v[68:83]
	ds_read_b128 v[180:183], v225 offset:272
	s_waitcnt lgkmcnt(3)
	v_mfma_f32_32x32x16_bf16 v[68:83], v[232:235], v[104:107], v[68:83]
	ds_read_b128 v[184:187], v225 offset:304
	s_waitcnt lgkmcnt(3)
	v_mfma_f32_32x32x16_bf16 v[68:83], v[172:175], v[108:111], v[68:83]
	ds_read_b128 v[232:235], v225 offset:336
	s_waitcnt lgkmcnt(3)
	v_mfma_f32_32x32x16_bf16 v[68:83], v[176:179], v[112:115], v[68:83]
	ds_read_b128 v[172:175], v225 offset:368
	s_waitcnt lgkmcnt(3)
	v_mfma_f32_32x32x16_bf16 v[68:83], v[180:183], v[116:119], v[68:83]
	s_waitcnt lgkmcnt(2)
	v_mfma_f32_32x32x16_bf16 v[68:83], v[184:187], v[120:123], v[68:83]
	s_waitcnt lgkmcnt(1)
	v_mfma_f32_32x32x16_bf16 v[68:83], v[232:235], v[124:127], v[68:83]
	s_waitcnt lgkmcnt(0)
	v_mfma_f32_32x32x16_bf16 v[68:83], v[172:175], v[128:131], v[68:83]
	v_add_u32_e32 v3, 0x6000, v226
	ds_read2_b64 v[172:175], v3 offset0:130 offset1:132
	v_add_u32_e32 v3, 0x7000, v226
	ds_read2_b64 v[176:179], v3 offset0:162 offset1:164
	s_nop 7
	v_max_f32_e32 v3, v69, v69
	v_max_f32_e32 v180, v68, v68
	v_max_f32_e32 v3, v180, v3
	v_max3_f32 v3, v3, v70, v71
	v_max3_f32 v3, v3, v72, v73
	v_max3_f32 v3, v3, v74, v75
	v_max3_f32 v3, v3, v76, v77
	v_max3_f32 v3, v3, v78, v79
	v_max3_f32 v3, v3, v80, v81
	v_max3_f32 v3, v3, v82, v83
	v_mov_b32_e32 v218, v3
	v_mov_b32_e32 v180, v3
	v_add_u32_e32 v184, 0x8000, v226
	ds_read2_b64 v[184:187], v184 offset0:194 offset1:196
	v_permlane32_swap_b32_e32 v218, v180
	v_max_f32_e32 v218, v218, v180
	v_add_u32_e32 v180, 0x9000, v226
	ds_read2_b64 v[180:183], v180 offset0:226 offset1:228
	s_waitcnt lgkmcnt(2)
	v_max3_f32 v3, v231, v3, v218
	v_sub_f32_e32 v218, v231, v3
	v_exp_f32_e32 v218, v218
	v_cmp_gt_f32_e32 vcc, v3, v231
	s_cbranch_vccz .LBB0_644
	v_pk_mul_f32 v[66:67], v[66:67], v[218:219] op_sel_hi:[1,0]
	v_pk_mul_f32 v[64:65], v[64:65], v[218:219] op_sel_hi:[1,0]
	v_pk_mul_f32 v[62:63], v[62:63], v[218:219] op_sel_hi:[1,0]
	v_pk_mul_f32 v[60:61], v[60:61], v[218:219] op_sel_hi:[1,0]
	v_pk_mul_f32 v[58:59], v[58:59], v[218:219] op_sel_hi:[1,0]
	v_pk_mul_f32 v[56:57], v[56:57], v[218:219] op_sel_hi:[1,0]
	v_pk_mul_f32 v[54:55], v[54:55], v[218:219] op_sel_hi:[1,0]
	v_pk_mul_f32 v[52:53], v[52:53], v[218:219] op_sel_hi:[1,0]
	v_pk_mul_f32 v[50:51], v[50:51], v[218:219] op_sel_hi:[1,0]
	v_pk_mul_f32 v[48:49], v[48:49], v[218:219] op_sel_hi:[1,0]
	v_pk_mul_f32 v[46:47], v[46:47], v[218:219] op_sel_hi:[1,0]
	v_pk_mul_f32 v[44:45], v[44:45], v[218:219] op_sel_hi:[1,0]
	v_pk_mul_f32 v[42:43], v[42:43], v[218:219] op_sel_hi:[1,0]
	v_pk_mul_f32 v[40:41], v[40:41], v[218:219] op_sel_hi:[1,0]
	v_pk_mul_f32 v[38:39], v[38:39], v[218:219] op_sel_hi:[1,0]
	v_pk_mul_f32 v[36:37], v[36:37], v[218:219] op_sel_hi:[1,0]
	v_pk_mul_f32 v[34:35], v[34:35], v[218:219] op_sel_hi:[1,0]
	v_pk_mul_f32 v[32:33], v[32:33], v[218:219] op_sel_hi:[1,0]
	v_pk_mul_f32 v[30:31], v[30:31], v[218:219] op_sel_hi:[1,0]
	v_pk_mul_f32 v[28:29], v[28:29], v[218:219] op_sel_hi:[1,0]
	v_pk_mul_f32 v[26:27], v[26:27], v[218:219] op_sel_hi:[1,0]
	v_pk_mul_f32 v[24:25], v[24:25], v[218:219] op_sel_hi:[1,0]
	v_pk_mul_f32 v[22:23], v[22:23], v[218:219] op_sel_hi:[1,0]
	v_pk_mul_f32 v[20:21], v[20:21], v[218:219] op_sel_hi:[1,0]
	v_pk_mul_f32 v[18:19], v[18:19], v[218:219] op_sel_hi:[1,0]
	v_pk_mul_f32 v[16:17], v[16:17], v[218:219] op_sel_hi:[1,0]
	v_pk_mul_f32 v[14:15], v[14:15], v[218:219] op_sel_hi:[1,0]
	v_pk_mul_f32 v[12:13], v[12:13], v[218:219] op_sel_hi:[1,0]
	v_pk_mul_f32 v[10:11], v[10:11], v[218:219] op_sel_hi:[1,0]
	v_pk_mul_f32 v[8:9], v[8:9], v[218:219] op_sel_hi:[1,0]
	v_pk_mul_f32 v[6:7], v[6:7], v[218:219] op_sel_hi:[1,0]
	v_pk_mul_f32 v[4:5], v[4:5], v[218:219] op_sel_hi:[1,0]
